# grid barrier: non-leader workgroups poll the top generation word directly; leader no longer bumps the per-XCD generation word
# speedup vs baseline: 1.0947x; 1.0074x over previous
.LBB0_1040:
	s_add_i32 s14, s12, -1
	s_bitcmp1_b32 s14, 0
	s_cselect_b32 s13, 0x9000, 0
	s_bitcmp1_b32 s12, 0
	s_cselect_b32 s15, 0x9000, 0
	v_lshlrev_b32_e32 v112, 1, v151
	v_lshlrev_b32_e32 v113, 1, v146
	v_add3_u32 v112, s15, v112, v113
	s_waitcnt vmcnt(7)
	ds_write_b128 v112, v[16:19]
	v_lshlrev_b32_e32 v16, 1, v153
	v_lshlrev_b32_e32 v17, 1, v152
	v_add3_u32 v16, s15, v16, v17
	s_waitcnt vmcnt(5)
	ds_write_b128 v16, v[20:23]
	v_lshlrev_b32_e32 v16, 1, v155
	v_lshlrev_b32_e32 v17, 1, v156
	v_add3_u32 v16, s15, v16, v17
	ds_write_b128 v16, v[32:35]
	v_lshlrev_b32_e32 v16, 1, v157
	v_lshlrev_b32_e32 v17, 1, v160
	v_add3_u32 v16, s15, v16, v17
	s_waitcnt vmcnt(4)
	ds_write_b128 v16, v[44:47]
	v_lshlrev_b32_e32 v16, 1, v159
	v_lshlrev_b32_e32 v17, 1, v162
	v_add3_u32 v16, s15, v16, v17
	s_waitcnt vmcnt(3)
	ds_write_b128 v16, v[60:63] offset:18432
	v_lshlrev_b32_e32 v16, 1, v161
	v_lshlrev_b32_e32 v17, 1, v166
	v_add3_u32 v16, s15, v16, v17
	s_waitcnt vmcnt(2)
	ds_write_b128 v16, v[52:55] offset:18432
	v_lshlrev_b32_e32 v16, 1, v163
	v_lshlrev_b32_e32 v17, 1, v170
	v_add3_u32 v16, s15, v16, v17
	s_waitcnt vmcnt(1)
	ds_write_b128 v16, v[56:59] offset:18432
	v_lshlrev_b32_e32 v16, 1, v167
	v_lshlrev_b32_e32 v17, 1, v174
	s_min_u32 s14, s14, 17
	v_add3_u32 v16, s15, v16, v17
	s_lshl_b32 s15, s14, 6
	s_addk_i32 s15, 0x80
	s_waitcnt vmcnt(0)
	ds_write_b128 v16, v[48:51] offset:18432
	v_add_u32_e32 v16, s15, v144
	v_add_u32_e32 v18, s15, v150
	v_add_u32_e32 v32, s15, v154
	v_add_u32_e32 v34, s15, v158
	v_ashrrev_i32_e32 v17, 31, v16
	v_ashrrev_i32_e32 v19, 31, v18
	v_ashrrev_i32_e32 v33, 31, v32
	v_ashrrev_i32_e32 v35, 31, v34
	v_lshlrev_b64 v[16:17], 11, v[16:17]
	v_lshlrev_b64 v[18:19], 11, v[18:19]
	v_lshlrev_b64 v[32:33], 11, v[32:33]
	v_lshlrev_b64 v[34:35], 11, v[34:35]
	s_lshl_b32 s36, s14, 7
	v_lshl_add_u64 v[16:17], v[180:181], 0, v[16:17]
	v_lshl_add_u64 v[20:21], v[182:183], 0, v[18:19]
	v_lshl_add_u64 v[32:33], v[184:185], 0, v[32:33]
	v_lshl_add_u64 v[44:45], v[186:187], 0, v[34:35]
	v_lshl_add_u64 v[48:49], v[164:165], 0, s[36:37]
	v_lshl_add_u64 v[50:51], v[168:169], 0, s[36:37]
	global_load_dwordx4 v[16:19], v[16:17], off
	s_nop 0
	global_load_dwordx4 v[20:23], v[20:21], off
	s_nop 0
	global_load_dwordx4 v[32:35], v[32:33], off
	s_nop 0
	global_load_dwordx4 v[44:47], v[44:45], off
	s_nop 0
	global_load_dwordx4 v[60:63], v[48:49], off offset:256
	global_load_dwordx4 v[52:55], v[50:51], off offset:256
	v_lshl_add_u64 v[48:49], v[172:173], 0, s[36:37]
	v_lshl_add_u64 v[50:51], v[178:179], 0, s[36:37]
	global_load_dwordx4 v[56:59], v[48:49], off offset:256
	s_nop 0
	global_load_dwordx4 v[48:51], v[50:51], off offset:256
	v_lshlrev_b32_e32 v116, 1, v214
	v_add3_u32 v217, s13, v211, v116
	ds_read_b128 v[226:229], v217
	ds_read_b128 v[230:233], v217 offset:128
	ds_read_b128 v[234:237], v217 offset:4608
	ds_read_b128 v[242:245], v217 offset:4736
	ds_read_b128 v[246:249], v217 offset:9216
	v_xor_b32_e32 v112, 0x80000000, v213
	v_xor_b32_e32 v128, 0x80000000, v212
	v_mov_b32_e32 v113, v112
	v_mov_b32_e32 v114, v112
	v_mov_b32_e32 v115, v112
	v_mov_b32_e32 v129, v128
	v_mov_b32_e32 v130, v128
	v_mov_b32_e32 v131, v128
	ds_read_b128 v[204:207], v217 offset:9344
	s_waitcnt lgkmcnt(5)
	v_mfma_f32_16x16x32_bf16 v[116:119], v[226:229], v[12:15], v[112:115]
	ds_read_b128 v[226:229], v217 offset:13824
	s_waitcnt lgkmcnt(5)
	v_mfma_f32_16x16x32_bf16 v[120:123], v[230:233], v[8:11], v[128:131]
	ds_read_b128 v[230:233], v217 offset:13952
	s_waitcnt lgkmcnt(5)
	v_mfma_f32_16x16x32_bf16 v[190:193], v[234:237], v[12:15], v[112:115]
	ds_read_b128 v[234:237], v217 offset:64
	s_waitcnt lgkmcnt(5)
	v_mfma_f32_16x16x32_bf16 v[132:135], v[242:245], v[8:11], v[128:131]
	ds_read_b128 v[242:245], v217 offset:192
	s_waitcnt lgkmcnt(5)
	v_mfma_f32_16x16x32_bf16 v[194:197], v[246:249], v[12:15], v[112:115]
	ds_read_b128 v[246:249], v217 offset:4672
	s_waitcnt lgkmcnt(5)
	v_mfma_f32_16x16x32_bf16 v[198:201], v[204:207], v[8:11], v[128:131]
	ds_read_b128 v[204:207], v217 offset:4800
	s_waitcnt lgkmcnt(5)
	v_mfma_f32_16x16x32_bf16 v[112:115], v[226:229], v[12:15], v[112:115]
	ds_read_b128 v[226:229], v217 offset:9280
	s_waitcnt lgkmcnt(5)
	v_mfma_f32_16x16x32_bf16 v[218:221], v[230:233], v[8:11], v[128:131]
	ds_read_b128 v[230:233], v217 offset:9408
	s_waitcnt lgkmcnt(5)
	v_mfma_f32_16x16x32_bf16 v[140:143], v[234:237], v[4:7], v[116:119]
	ds_read_b128 v[234:237], v217 offset:13888
	s_waitcnt lgkmcnt(5)
	v_mfma_f32_16x16x32_bf16 v[124:127], v[242:245], v[0:3], v[120:123]
	ds_read_b128 v[242:245], v217 offset:14016
	s_waitcnt lgkmcnt(5)
	v_mfma_f32_16x16x32_bf16 v[136:139], v[246:249], v[4:7], v[190:193]
	s_waitcnt lgkmcnt(4)
	v_mfma_f32_16x16x32_bf16 v[120:123], v[204:207], v[0:3], v[132:135]
	s_waitcnt lgkmcnt(3)
	v_mfma_f32_16x16x32_bf16 v[132:135], v[226:229], v[4:7], v[194:197]
	s_waitcnt lgkmcnt(2)
	v_mfma_f32_16x16x32_bf16 v[116:119], v[230:233], v[0:3], v[198:201]
	s_waitcnt lgkmcnt(1)
	v_mfma_f32_16x16x32_bf16 v[128:131], v[234:237], v[4:7], v[112:115]
	s_waitcnt lgkmcnt(0)
	v_mfma_f32_16x16x32_bf16 v[112:115], v[242:245], v[0:3], v[218:221]
	v_max_f32_e32 v190, v141, v141
	v_max_f32_e32 v191, v140, v140
	v_max_f32_e32 v204, v125, v125
	v_max_f32_e32 v205, v124, v124
	v_max_f32_e32 v190, v191, v190
	v_max_f32_e32 v204, v205, v204
	v_max3_f32 v190, v190, v142, v143
	v_max3_f32 v204, v204, v126, v127
	v_max3_f32 v190, v190, v136, v137
	v_max3_f32 v204, v204, v120, v121
	v_max3_f32 v190, v190, v138, v139
	v_max3_f32 v204, v204, v122, v123
	v_max3_f32 v190, v190, v132, v133
	v_max3_f32 v204, v204, v116, v117
	v_max3_f32 v190, v190, v134, v135
	v_max3_f32 v204, v204, v118, v119
	v_max3_f32 v190, v190, v128, v129
	v_max3_f32 v204, v204, v112, v113
	v_max3_f32 v190, v190, v130, v131
	v_max3_f32 v204, v204, v114, v115
	ds_bpermute_b32 v191, v145, v190
	ds_bpermute_b32 v205, v145, v204
	s_waitcnt lgkmcnt(0)
	v_max_f32_e32 v191, v191, v191
	v_max_f32_e32 v205, v205, v205
	v_max_f32_e32 v190, v190, v191
	v_max_f32_e32 v204, v204, v205
	ds_bpermute_b32 v191, v147, v190
	ds_bpermute_b32 v205, v147, v204
	s_waitcnt lgkmcnt(0)
	v_max_f32_e32 v191, v191, v191
	v_max_f32_e32 v205, v205, v205
	v_max_f32_e32 v217, v190, v191
	v_max_f32_e32 v206, v204, v205
	v_cmp_lt_f32_e32 vcc, s79, v217
	s_cbranch_vccz .LBB0_1042
	s_nop 0
	v_cndmask_b32_e32 v191, 0, v217, vcc
	v_exp_f32_e64 v190, -v191
	v_add_f32_e32 v213, v213, v191
	v_sub_f32_e32 v140, v140, v191
	v_sub_f32_e32 v141, v141, v191
	v_pk_mul_f32 v[30:31], v[30:31], v[190:191] op_sel_hi:[1,0]
	v_pk_mul_f32 v[28:29], v[28:29], v[190:191] op_sel_hi:[1,0]
	v_pk_mul_f32 v[42:43], v[42:43], v[190:191] op_sel_hi:[1,0]
	v_pk_mul_f32 v[40:41], v[40:41], v[190:191] op_sel_hi:[1,0]
	v_pk_mul_f32 v[70:71], v[70:71], v[190:191] op_sel_hi:[1,0]
	v_pk_mul_f32 v[68:69], v[68:69], v[190:191] op_sel_hi:[1,0]
	v_pk_mul_f32 v[78:79], v[78:79], v[190:191] op_sel_hi:[1,0]
	v_pk_mul_f32 v[76:77], v[76:77], v[190:191] op_sel_hi:[1,0]
	v_pk_mul_f32 v[86:87], v[86:87], v[190:191] op_sel_hi:[1,0]
	v_pk_mul_f32 v[84:85], v[84:85], v[190:191] op_sel_hi:[1,0]
	v_pk_mul_f32 v[94:95], v[94:95], v[190:191] op_sel_hi:[1,0]
	v_pk_mul_f32 v[92:93], v[92:93], v[190:191] op_sel_hi:[1,0]
	v_pk_mul_f32 v[102:103], v[102:103], v[190:191] op_sel_hi:[1,0]
	v_pk_mul_f32 v[100:101], v[100:101], v[190:191] op_sel_hi:[1,0]
	v_pk_mul_f32 v[110:111], v[110:111], v[190:191] op_sel_hi:[1,0]
	v_pk_mul_f32 v[108:109], v[108:109], v[190:191] op_sel_hi:[1,0]
	v_mul_f32_e32 v171, v171, v190
	v_sub_f32_e32 v142, v142, v191
	v_sub_f32_e32 v143, v143, v191
	v_sub_f32_e32 v136, v136, v191
	v_sub_f32_e32 v137, v137, v191
	v_sub_f32_e32 v138, v138, v191
	v_sub_f32_e32 v139, v139, v191
	v_sub_f32_e32 v132, v132, v191
	v_sub_f32_e32 v133, v133, v191
	v_sub_f32_e32 v134, v134, v191
	v_sub_f32_e32 v135, v135, v191
	v_sub_f32_e32 v128, v128, v191
	v_sub_f32_e32 v129, v129, v191
	v_sub_f32_e32 v130, v130, v191
	v_sub_f32_e32 v131, v131, v191

.LBB0_1459:
	s_or_b64 exec, exec, s[2:3]
	v_cvt_f32_u32_e32 v4, v2
	s_waitcnt vmcnt(0)
	v_readfirstlane_b32 s2, v3
	v_sub_u32_e32 v3, 0, v2
	v_rcp_iflag_f32_e32 v4, v4
	v_add_u32_e32 v5, s2, v1
	v_mul_f32_e32 v4, 0x4f7ffffe, v4
	v_cvt_u32_f32_e32 v4, v4
	v_mul_lo_u32 v1, v3, v4
	v_mul_hi_u32 v1, v4, v1
	v_add_u32_e32 v1, v4, v1
	v_mul_hi_u32 v1, v5, v1
	v_mul_lo_u32 v3, v1, v2
	v_sub_u32_e32 v3, v5, v3
	v_add_u32_e32 v4, 1, v1
	v_cmp_ge_u32_e32 vcc, v3, v2
	s_nop 1
	v_cndmask_b32_e32 v1, v1, v4, vcc
	v_sub_u32_e32 v4, v3, v2
	v_cndmask_b32_e32 v3, v3, v4, vcc
	v_add_u32_e32 v4, 1, v1
	v_cmp_ge_u32_e32 vcc, v3, v2
	v_add_u32_e32 v3, 1, v5
	s_nop 0
	v_cndmask_b32_e32 v1, v1, v4, vcc
	v_mul_lo_u32 v4, v2, v1
	v_add_u32_e32 v2, v4, v2
	v_cmp_ne_u32_e32 vcc, v3, v2
	s_and_saveexec_b64 s[2:3], vcc
	s_xor_b64 s[2:3], exec, s[2:3]
	s_cbranch_execz .LBB0_1473
	v_readlane_b32 s4, v254, 60
	v_readlane_b32 s5, v254, 61
	s_waitcnt lgkmcnt(0)
	s_nop 3
	global_load_dword v0, v177, s[4:5] sc1
	s_waitcnt vmcnt(0)
	v_cmp_eq_u32_e32 vcc, v0, v1
	s_and_saveexec_b64 s[4:5], vcc
	s_cbranch_execz .LBB0_1472
	s_mov_b32 s16, 1
	s_mov_b64 s[6:7], 0
	s_branch .LBB0_1463

.LBB0_1465:
	v_readlane_b32 s10, v254, 60
	v_readlane_b32 s11, v254, 61
	s_add_i32 s16, s16, 1
	s_mov_b64 s[12:13], -1
	s_nop 2
	global_load_dword v0, v177, s[10:11] sc1
	s_waitcnt vmcnt(0)
	v_cmp_ne_u32_e32 vcc, v0, v1
	s_orn2_b64 s[10:11], vcc, exec
	s_branch .LBB0_1462

.LBB0_1491:
	s_bcnt1_i32_b64 s2, s[2:3]
	v_mov_b32_e32 v0, s2
	v_readlane_b32 s2, v254, 56
	v_readlane_b32 s3, v254, 57
	s_nop 4
	s_nop 0
	s_getpc_b64 s[98:99]
